# split-K atomic tails: LDS-transposed atomics (each instr = 2 rows x 128B contiguous) on top of 4x/8x fan-out; +4KiB static LDS scratch
# speedup vs baseline: 1.0427x; 1.0188x over previous
.LBB0_546:
	s_add_i32 s10, s44, 0x100
	s_and_b64 s[8:9], s[42:43], exec
	s_cselect_b32 s9, 0, s10
	s_cselect_b32 s8, 0, 0
	s_add_u32 s46, s82, s9
	s_addc_u32 s47, s83, s8
	s_add_i32 s10, 0, 0x10000
	s_add_u32 s48, s38, s9
	s_addc_u32 s49, s39, s8
	s_add_i32 s8, 0, 0x14000
	s_add_u32 s54, s34, s44
	s_addc_u32 s55, s35, 0
	s_add_i32 s68, s10, s53
	s_add_i32 m0, s4, 0xc000
	s_add_i32 s9, s4, 0xe000
	s_add_i32 s65, s68, 0x2000
	s_add_u32 s50, s48, 0xb0000
	v_add_u32_e32 v148, s10, v134
	v_add_u32_e32 v164, s8, v134
	s_addc_u32 s51, s49, 0
	s_add_i32 s67, s8, s53
	ds_read_b128 v[136:139], v148
	ds_read_b128 v[140:143], v148 offset:1024
	ds_read_b128 v[144:147], v148 offset:2048
	ds_read_b128 v[148:151], v148 offset:3072
	ds_read_b128 v[152:155], v164
	ds_read_b128 v[156:159], v164 offset:1024
	ds_read_b128 v[160:163], v164 offset:2048
	ds_read_b128 v[164:167], v164 offset:3072
	s_add_i32 s66, s67, 0x2000
	s_add_i32 s64, 0, 0x18000
	s_add_i32 s63, 0, 0x1c000
	s_add_u32 s44, s46, 0xb0000
	s_addc_u32 s45, s47, 0
	s_add_i32 s62, s64, s53
	s_add_i32 s61, s62, 0x2000
	s_add_u32 s42, s48, 0xb0080
	s_addc_u32 s43, s49, 0
	s_add_i32 s72, s63, s53
	s_add_i32 s69, s72, 0x2000
	v_lshl_add_u64 v[202:203], s[54:55], 0, v[0:1]
	v_lshl_add_u64 v[202:203], v[202:203], 0, s[26:27]
	ds_read_b128 v[168:171], v135
	ds_read_b128 v[172:175], v135 offset:1024
	ds_read_b128 v[176:179], v135 offset:2048
	ds_read_b128 v[180:183], v135 offset:3072
	ds_read_b128 v[184:187], v135 offset:4096
	ds_read_b128 v[224:227], v135 offset:5120
	ds_read_b128 v[228:231], v135 offset:6144
	ds_read_b128 v[232:235], v135 offset:7168
	global_load_lds_dwordx4 v[202:203], off
	v_lshl_add_u64 v[202:203], s[54:55], 0, v[130:131]
	v_lshl_add_u64 v[202:203], v[202:203], 0, s[26:27]
	s_mov_b32 m0, s9
	s_nop 0
	global_load_lds_dwordx4 v[202:203], off
	s_waitcnt vmcnt(8)
	s_waitcnt lgkmcnt(0)
	s_barrier
	s_setprio 1
	s_waitcnt lgkmcnt(0)
	v_mfma_f32_16x16x32_bf16 v[126:129], v[136:139], v[168:171], v[126:129]
	v_mfma_f32_16x16x32_bf16 v[122:125], v[144:147], v[168:171], v[122:125]
	v_mfma_f32_16x16x32_bf16 v[118:121], v[136:139], v[176:179], v[118:121]
	v_mfma_f32_16x16x32_bf16 v[110:113], v[144:147], v[176:179], v[110:113]
	v_mfma_f32_16x16x32_bf16 v[102:105], v[136:139], v[184:187], v[102:105]
	v_mfma_f32_16x16x32_bf16 v[94:97], v[144:147], v[184:187], v[94:97]
	v_mfma_f32_16x16x32_bf16 v[86:89], v[136:139], v[228:231], v[86:89]
	v_mfma_f32_16x16x32_bf16 v[78:81], v[144:147], v[228:231], v[78:81]
	v_mfma_f32_16x16x32_bf16 v[126:129], v[140:143], v[172:175], v[126:129]
	v_mfma_f32_16x16x32_bf16 v[122:125], v[148:151], v[172:175], v[122:125]
	v_mfma_f32_16x16x32_bf16 v[118:121], v[140:143], v[180:183], v[118:121]
	v_mfma_f32_16x16x32_bf16 v[110:113], v[148:151], v[180:183], v[110:113]
	v_mfma_f32_16x16x32_bf16 v[102:105], v[140:143], v[224:227], v[102:105]
	v_mfma_f32_16x16x32_bf16 v[94:97], v[148:151], v[224:227], v[94:97]
	v_mfma_f32_16x16x32_bf16 v[86:89], v[140:143], v[232:235], v[86:89]
	v_mfma_f32_16x16x32_bf16 v[78:81], v[148:151], v[232:235], v[78:81]
	s_setprio 0
	s_setprio 1
	v_mfma_f32_16x16x32_bf16 v[114:117], v[152:155], v[168:171], v[114:117]
	v_mfma_f32_16x16x32_bf16 v[106:109], v[160:163], v[168:171], v[106:109]
	v_mfma_f32_16x16x32_bf16 v[98:101], v[152:155], v[176:179], v[98:101]
	v_mfma_f32_16x16x32_bf16 v[90:93], v[160:163], v[176:179], v[90:93]
	v_mfma_f32_16x16x32_bf16 v[82:85], v[152:155], v[184:187], v[82:85]
	v_mfma_f32_16x16x32_bf16 v[74:77], v[160:163], v[184:187], v[74:77]
	v_mfma_f32_16x16x32_bf16 v[70:73], v[152:155], v[228:231], v[70:73]
	v_mfma_f32_16x16x32_bf16 v[66:69], v[160:163], v[228:231], v[66:69]
	v_mfma_f32_16x16x32_bf16 v[114:117], v[156:159], v[172:175], v[114:117]
	v_mfma_f32_16x16x32_bf16 v[106:109], v[164:167], v[172:175], v[106:109]
	v_mfma_f32_16x16x32_bf16 v[98:101], v[156:159], v[180:183], v[98:101]
	v_mfma_f32_16x16x32_bf16 v[90:93], v[164:167], v[180:183], v[90:93]
	v_mfma_f32_16x16x32_bf16 v[82:85], v[156:159], v[224:227], v[82:85]
	v_mfma_f32_16x16x32_bf16 v[74:77], v[164:167], v[224:227], v[74:77]
	v_mfma_f32_16x16x32_bf16 v[70:73], v[156:159], v[232:235], v[70:73]
	v_mfma_f32_16x16x32_bf16 v[66:69], v[164:167], v[232:235], v[66:69]
	s_setprio 0
	s_barrier
	s_mov_b32 m0, s68
	v_lshl_add_u64 v[202:203], s[48:49], 0, v[0:1]
	ds_read_b128 v[168:171], v135 offset:16384
	ds_read_b128 v[172:175], v135 offset:17408
	ds_read_b128 v[176:179], v135 offset:18432
	ds_read_b128 v[180:183], v135 offset:19456
	ds_read_b128 v[184:187], v135 offset:20480
	ds_read_b128 v[224:227], v135 offset:21504
	ds_read_b128 v[228:231], v135 offset:22528
	ds_read_b128 v[232:235], v135 offset:23552
	global_load_lds_dwordx4 v[202:203], off
	v_lshl_add_u64 v[236:237], s[48:49], 0, v[130:131]
	s_mov_b32 m0, s65
	v_lshl_add_u64 v[238:239], s[50:51], 0, v[0:1]
	global_load_lds_dwordx4 v[236:237], off
	s_mov_b32 m0, s67
	v_lshl_add_u64 v[240:241], s[46:47], 0, v[130:131]
	global_load_lds_dwordx4 v[238:239], off
	v_lshl_add_u64 v[238:239], s[50:51], 0, v[130:131]
	s_mov_b32 m0, s66
	s_nop 0
	global_load_lds_dwordx4 v[238:239], off
	v_lshl_add_u64 v[238:239], s[46:47], 0, v[0:1]
	s_mov_b32 m0, s4
	s_nop 0
	global_load_lds_dwordx4 v[238:239], off
	s_mov_b32 m0, s5
	s_nop 0
	global_load_lds_dwordx4 v[240:241], off
	s_waitcnt vmcnt(8)
	s_waitcnt lgkmcnt(0)
	s_barrier
	s_setprio 1
	s_waitcnt lgkmcnt(0)
	v_mfma_f32_16x16x32_bf16 v[62:65], v[136:139], v[168:171], v[62:65]
	v_mfma_f32_16x16x32_bf16 v[58:61], v[144:147], v[168:171], v[58:61]
	v_mfma_f32_16x16x32_bf16 v[54:57], v[136:139], v[176:179], v[54:57]
	v_mfma_f32_16x16x32_bf16 v[46:49], v[144:147], v[176:179], v[46:49]
	v_mfma_f32_16x16x32_bf16 v[38:41], v[136:139], v[184:187], v[38:41]
	v_mfma_f32_16x16x32_bf16 v[30:33], v[144:147], v[184:187], v[30:33]
	v_mfma_f32_16x16x32_bf16 v[22:25], v[136:139], v[228:231], v[22:25]
	v_mfma_f32_16x16x32_bf16 v[14:17], v[144:147], v[228:231], v[14:17]
	v_mfma_f32_16x16x32_bf16 v[62:65], v[140:143], v[172:175], v[62:65]
	v_mfma_f32_16x16x32_bf16 v[58:61], v[148:151], v[172:175], v[58:61]
	v_mfma_f32_16x16x32_bf16 v[54:57], v[140:143], v[180:183], v[54:57]
	v_mfma_f32_16x16x32_bf16 v[46:49], v[148:151], v[180:183], v[46:49]
	v_mfma_f32_16x16x32_bf16 v[38:41], v[140:143], v[224:227], v[38:41]
	v_mfma_f32_16x16x32_bf16 v[30:33], v[148:151], v[224:227], v[30:33]
	v_mfma_f32_16x16x32_bf16 v[22:25], v[140:143], v[232:235], v[22:25]
	v_mfma_f32_16x16x32_bf16 v[14:17], v[148:151], v[232:235], v[14:17]
	s_setprio 0
	s_setprio 1
	v_mfma_f32_16x16x32_bf16 v[50:53], v[152:155], v[168:171], v[50:53]
	v_mfma_f32_16x16x32_bf16 v[42:45], v[160:163], v[168:171], v[42:45]
	v_mfma_f32_16x16x32_bf16 v[34:37], v[152:155], v[176:179], v[34:37]
	v_mfma_f32_16x16x32_bf16 v[26:29], v[160:163], v[176:179], v[26:29]
	v_mfma_f32_16x16x32_bf16 v[18:21], v[152:155], v[184:187], v[18:21]
	v_mfma_f32_16x16x32_bf16 v[10:13], v[160:163], v[184:187], v[10:13]
	v_mfma_f32_16x16x32_bf16 v[6:9], v[152:155], v[228:231], v[6:9]
	v_mfma_f32_16x16x32_bf16 v[2:5], v[160:163], v[228:231], v[2:5]
	v_mfma_f32_16x16x32_bf16 v[50:53], v[156:159], v[172:175], v[50:53]
	v_mfma_f32_16x16x32_bf16 v[42:45], v[164:167], v[172:175], v[42:45]
	v_mfma_f32_16x16x32_bf16 v[34:37], v[156:159], v[180:183], v[34:37]
	v_mfma_f32_16x16x32_bf16 v[26:29], v[164:167], v[180:183], v[26:29]
	v_mfma_f32_16x16x32_bf16 v[18:21], v[156:159], v[224:227], v[18:21]
	v_mfma_f32_16x16x32_bf16 v[10:13], v[164:167], v[224:227], v[10:13]
	v_mfma_f32_16x16x32_bf16 v[6:9], v[156:159], v[232:235], v[6:9]
	v_mfma_f32_16x16x32_bf16 v[2:5], v[164:167], v[232:235], v[2:5]
	s_setprio 0
	s_barrier
	v_add_u32_e32 v148, s64, v134
	v_add_u32_e32 v164, s63, v134
	ds_read_b128 v[136:139], v148
	ds_read_b128 v[140:143], v148 offset:1024
	ds_read_b128 v[144:147], v148 offset:2048
	ds_read_b128 v[148:151], v148 offset:3072
	ds_read_b128 v[152:155], v164
	ds_read_b128 v[156:159], v164 offset:1024
	ds_read_b128 v[160:163], v164 offset:2048
	ds_read_b128 v[164:167], v164 offset:3072
	s_mov_b32 m0, s56
	v_lshl_add_u64 v[242:243], s[44:45], 0, v[0:1]
	ds_read_b128 v[168:171], v135 offset:32768
	ds_read_b128 v[172:175], v135 offset:33792
	ds_read_b128 v[176:179], v135 offset:34816
	ds_read_b128 v[180:183], v135 offset:35840
	ds_read_b128 v[184:187], v135 offset:36864
	ds_read_b128 v[224:227], v135 offset:37888
	ds_read_b128 v[228:231], v135 offset:38912
	ds_read_b128 v[232:235], v135 offset:39936
	global_load_lds_dwordx4 v[242:243], off
	v_lshl_add_u64 v[242:243], s[44:45], 0, v[130:131]
	s_mov_b32 m0, s57
	s_nop 0
	global_load_lds_dwordx4 v[242:243], off
	s_waitcnt vmcnt(8)
	s_waitcnt lgkmcnt(0)
	s_barrier
	s_setprio 1
	s_waitcnt lgkmcnt(0)
	v_mfma_f32_16x16x32_bf16 v[126:129], v[136:139], v[168:171], v[126:129]
	v_mfma_f32_16x16x32_bf16 v[122:125], v[144:147], v[168:171], v[122:125]
	v_mfma_f32_16x16x32_bf16 v[118:121], v[136:139], v[176:179], v[118:121]
	v_mfma_f32_16x16x32_bf16 v[110:113], v[144:147], v[176:179], v[110:113]
	v_mfma_f32_16x16x32_bf16 v[102:105], v[136:139], v[184:187], v[102:105]
	v_mfma_f32_16x16x32_bf16 v[94:97], v[144:147], v[184:187], v[94:97]
	v_mfma_f32_16x16x32_bf16 v[86:89], v[136:139], v[228:231], v[86:89]
	v_mfma_f32_16x16x32_bf16 v[78:81], v[144:147], v[228:231], v[78:81]
	v_mfma_f32_16x16x32_bf16 v[126:129], v[140:143], v[172:175], v[126:129]
	v_mfma_f32_16x16x32_bf16 v[122:125], v[148:151], v[172:175], v[122:125]
	v_mfma_f32_16x16x32_bf16 v[118:121], v[140:143], v[180:183], v[118:121]
	v_mfma_f32_16x16x32_bf16 v[110:113], v[148:151], v[180:183], v[110:113]
	v_mfma_f32_16x16x32_bf16 v[102:105], v[140:143], v[224:227], v[102:105]
	v_mfma_f32_16x16x32_bf16 v[94:97], v[148:151], v[224:227], v[94:97]
	v_mfma_f32_16x16x32_bf16 v[86:89], v[140:143], v[232:235], v[86:89]
	v_mfma_f32_16x16x32_bf16 v[78:81], v[148:151], v[232:235], v[78:81]
	s_setprio 0
	s_setprio 1
	v_mfma_f32_16x16x32_bf16 v[114:117], v[152:155], v[168:171], v[114:117]
	v_mfma_f32_16x16x32_bf16 v[106:109], v[160:163], v[168:171], v[106:109]
	v_mfma_f32_16x16x32_bf16 v[98:101], v[152:155], v[176:179], v[98:101]
	v_mfma_f32_16x16x32_bf16 v[90:93], v[160:163], v[176:179], v[90:93]
	v_mfma_f32_16x16x32_bf16 v[82:85], v[152:155], v[184:187], v[82:85]
	v_mfma_f32_16x16x32_bf16 v[74:77], v[160:163], v[184:187], v[74:77]
	v_mfma_f32_16x16x32_bf16 v[70:73], v[152:155], v[228:231], v[70:73]
	v_mfma_f32_16x16x32_bf16 v[66:69], v[160:163], v[228:231], v[66:69]
	v_mfma_f32_16x16x32_bf16 v[114:117], v[156:159], v[172:175], v[114:117]
	v_mfma_f32_16x16x32_bf16 v[106:109], v[164:167], v[172:175], v[106:109]
	v_mfma_f32_16x16x32_bf16 v[98:101], v[156:159], v[180:183], v[98:101]
	v_mfma_f32_16x16x32_bf16 v[90:93], v[164:167], v[180:183], v[90:93]
	v_mfma_f32_16x16x32_bf16 v[82:85], v[156:159], v[224:227], v[82:85]
	v_mfma_f32_16x16x32_bf16 v[74:77], v[164:167], v[224:227], v[74:77]
	v_mfma_f32_16x16x32_bf16 v[70:73], v[156:159], v[232:235], v[70:73]
	v_mfma_f32_16x16x32_bf16 v[66:69], v[164:167], v[232:235], v[66:69]
	s_setprio 0
	s_barrier
	s_mov_b32 m0, s62
	v_lshl_add_u64 v[202:203], v[202:203], 0, s[26:27]
	ds_read_b128 v[168:171], v135 offset:49152
	ds_read_b128 v[172:175], v135 offset:50176
	ds_read_b128 v[176:179], v135 offset:51200
	ds_read_b128 v[180:183], v135 offset:52224
	ds_read_b128 v[184:187], v135 offset:53248
	ds_read_b128 v[224:227], v135 offset:54272
	ds_read_b128 v[228:231], v135 offset:55296
	ds_read_b128 v[232:235], v135 offset:56320
	global_load_lds_dwordx4 v[202:203], off
	v_lshl_add_u64 v[202:203], v[236:237], 0, s[26:27]
	s_mov_b32 m0, s61
	s_nop 0
	global_load_lds_dwordx4 v[202:203], off
	v_lshl_add_u64 v[202:203], s[42:43], 0, v[0:1]
	s_mov_b32 m0, s72
	s_nop 0
	global_load_lds_dwordx4 v[202:203], off
	v_lshl_add_u64 v[202:203], s[42:43], 0, v[130:131]
	s_mov_b32 m0, s69
	s_nop 0
	global_load_lds_dwordx4 v[202:203], off
	v_lshl_add_u64 v[202:203], v[238:239], 0, s[26:27]
	s_mov_b32 m0, s59
	s_nop 0
	global_load_lds_dwordx4 v[202:203], off
	v_lshl_add_u64 v[202:203], v[240:241], 0, s[26:27]
	s_mov_b32 m0, s60
	s_nop 0
	global_load_lds_dwordx4 v[202:203], off
	s_waitcnt vmcnt(8)
	s_waitcnt lgkmcnt(0)
	s_barrier
	s_setprio 1
	s_waitcnt lgkmcnt(0)
	v_mfma_f32_16x16x32_bf16 v[62:65], v[136:139], v[168:171], v[62:65]
	v_mfma_f32_16x16x32_bf16 v[58:61], v[144:147], v[168:171], v[58:61]
	v_mfma_f32_16x16x32_bf16 v[54:57], v[136:139], v[176:179], v[54:57]
	v_mfma_f32_16x16x32_bf16 v[46:49], v[144:147], v[176:179], v[46:49]
	v_mfma_f32_16x16x32_bf16 v[38:41], v[136:139], v[184:187], v[38:41]
	v_mfma_f32_16x16x32_bf16 v[30:33], v[144:147], v[184:187], v[30:33]
	v_mfma_f32_16x16x32_bf16 v[22:25], v[136:139], v[228:231], v[22:25]
	v_mfma_f32_16x16x32_bf16 v[14:17], v[144:147], v[228:231], v[14:17]
	v_mfma_f32_16x16x32_bf16 v[62:65], v[140:143], v[172:175], v[62:65]
	v_mfma_f32_16x16x32_bf16 v[58:61], v[148:151], v[172:175], v[58:61]
	v_mfma_f32_16x16x32_bf16 v[54:57], v[140:143], v[180:183], v[54:57]
	v_mfma_f32_16x16x32_bf16 v[46:49], v[148:151], v[180:183], v[46:49]
	v_mfma_f32_16x16x32_bf16 v[38:41], v[140:143], v[224:227], v[38:41]
	v_mfma_f32_16x16x32_bf16 v[30:33], v[148:151], v[224:227], v[30:33]
	v_mfma_f32_16x16x32_bf16 v[22:25], v[140:143], v[232:235], v[22:25]
	v_mfma_f32_16x16x32_bf16 v[14:17], v[148:151], v[232:235], v[14:17]
	s_setprio 0
	s_setprio 1
	v_mfma_f32_16x16x32_bf16 v[50:53], v[152:155], v[168:171], v[50:53]
	v_mfma_f32_16x16x32_bf16 v[42:45], v[160:163], v[168:171], v[42:45]
	v_mfma_f32_16x16x32_bf16 v[34:37], v[152:155], v[176:179], v[34:37]
	v_mfma_f32_16x16x32_bf16 v[26:29], v[160:163], v[176:179], v[26:29]
	v_mfma_f32_16x16x32_bf16 v[18:21], v[152:155], v[184:187], v[18:21]
	v_mfma_f32_16x16x32_bf16 v[10:13], v[160:163], v[184:187], v[10:13]
	v_mfma_f32_16x16x32_bf16 v[6:9], v[152:155], v[228:231], v[6:9]
	v_mfma_f32_16x16x32_bf16 v[2:5], v[160:163], v[228:231], v[2:5]
	v_mfma_f32_16x16x32_bf16 v[50:53], v[156:159], v[172:175], v[50:53]
	v_mfma_f32_16x16x32_bf16 v[42:45], v[164:167], v[172:175], v[42:45]
	v_mfma_f32_16x16x32_bf16 v[34:37], v[156:159], v[180:183], v[34:37]
	v_mfma_f32_16x16x32_bf16 v[26:29], v[164:167], v[180:183], v[26:29]
	v_mfma_f32_16x16x32_bf16 v[18:21], v[156:159], v[224:227], v[18:21]
	v_mfma_f32_16x16x32_bf16 v[10:13], v[164:167], v[224:227], v[10:13]
	v_mfma_f32_16x16x32_bf16 v[6:9], v[156:159], v[232:235], v[6:9]
	v_mfma_f32_16x16x32_bf16 v[2:5], v[164:167], v[232:235], v[2:5]
	s_setprio 0
	s_barrier
	s_andn2_b64 vcc, exec, s[40:41]
	s_mov_b64 s[42:43], -1
	s_mov_b64 s[40:41], 0
	s_movk_i32 s44, 0x100
	s_cbranch_vccz .LBB0_546
	v_readlane_b32 s4, v254, 17
	s_mul_i32 s5, s2, 0x5d2
	s_lshr_b32 s5, s5, 16
	v_and_b32_e32 v0, 63, v204
	v_lshrrev_b32_e32 v130, 5, v0
	v_and_b32_e32 v131, 31, v0
	s_lshr_b32 vcc_lo, s52, 8
	s_lshl_b32 vcc_lo, vcc_lo, 6
	v_add_u32_e32 v134, vcc_lo, v130
	v_lshlrev_b32_e32 v134, 12, v134
	s_or_b32 vcc_hi, s4, s58
	v_or_b32_e32 v135, vcc_hi, v131
	v_lshl_add_u32 v134, v135, 2, v134
	v_add_u32_e32 v134, 0x8000000, v134
	s_lshr_b32 vcc_lo, s52, 6
	s_mul_i32 vcc_lo, vcc_lo, 0x900
	s_add_u32 vcc_lo, vcc_lo, 0x20200
	v_and_b32_e32 v136, 15, v132
	v_mul_u32_u24_e32 v136, 0x90, v136
	v_lshl_add_u32 v136, v133, 4, v136
	v_add_u32_e32 v136, vcc_lo, v136
	v_mul_u32_u24_e32 v137, 0x90, v130
	v_lshl_add_u32 v137, v131, 2, v137
	v_add_u32_e32 v137, vcc_lo, v137
	s_cmp_lg_u32 s5, 0
	s_cbranch_scc1 .Lg2s_q1
	v_mov_b32_e32 v138, v134
	v_add_u32_e32 v139, 0x2000, v134
	v_add_u32_e32 v140, 0x4000, v134
	v_add_u32_e32 v141, 0x6000, v134
	v_add_u32_e32 v142, 0x8000, v134
	v_add_u32_e32 v143, 0xa000, v134
	v_add_u32_e32 v144, 0xc000, v134
	v_add_u32_e32 v145, 0xe000, v134
	v_pk_mul_f32 v[126:127], v[126:127], 0.5 op_sel_hi:[1,0]
	v_pk_mul_f32 v[128:129], v[128:129], 0.5 op_sel_hi:[1,0]
	v_pk_mul_f32 v[122:123], v[122:123], 0.5 op_sel_hi:[1,0]
	v_pk_mul_f32 v[124:125], v[124:125], 0.5 op_sel_hi:[1,0]
	ds_write_b128 v136, v[126:129]
	ds_write_b128 v136, v[122:125] offset:64
	ds_read_b32 v146, v137
	ds_read_b32 v147, v137 offset:288
	ds_read_b32 v148, v137 offset:576
	ds_read_b32 v149, v137 offset:864
	ds_read_b32 v150, v137 offset:1152
	ds_read_b32 v151, v137 offset:1440
	ds_read_b32 v152, v137 offset:1728
	ds_read_b32 v153, v137 offset:2016
	s_waitcnt lgkmcnt(0)
	global_atomic_add_f32 v138, v146, s[24:25]
	global_atomic_add_f32 v139, v147, s[24:25]
	global_atomic_add_f32 v140, v148, s[24:25]
	global_atomic_add_f32 v141, v149, s[24:25]
	global_atomic_add_f32 v142, v150, s[24:25]
	global_atomic_add_f32 v143, v151, s[24:25]
	global_atomic_add_f32 v144, v152, s[24:25]
	global_atomic_add_f32 v145, v153, s[24:25]
	v_pk_mul_f32 v[114:115], v[114:115], 0.5 op_sel_hi:[1,0]
	v_pk_mul_f32 v[116:117], v[116:117], 0.5 op_sel_hi:[1,0]
	v_pk_mul_f32 v[106:107], v[106:107], 0.5 op_sel_hi:[1,0]
	v_pk_mul_f32 v[108:109], v[108:109], 0.5 op_sel_hi:[1,0]
	ds_write_b128 v136, v[114:117]
	ds_write_b128 v136, v[106:109] offset:64
	ds_read_b32 v154, v137
	ds_read_b32 v155, v137 offset:288
	ds_read_b32 v156, v137 offset:576
	ds_read_b32 v157, v137 offset:864
	ds_read_b32 v158, v137 offset:1152
	ds_read_b32 v159, v137 offset:1440
	ds_read_b32 v160, v137 offset:1728
	ds_read_b32 v161, v137 offset:2016
	s_waitcnt lgkmcnt(0)
	global_atomic_add_f32 v138, v154, s[24:25] offset:512
	global_atomic_add_f32 v139, v155, s[24:25] offset:512
	global_atomic_add_f32 v140, v156, s[24:25] offset:512
	global_atomic_add_f32 v141, v157, s[24:25] offset:512
	global_atomic_add_f32 v142, v158, s[24:25] offset:512
	global_atomic_add_f32 v143, v159, s[24:25] offset:512
	global_atomic_add_f32 v144, v160, s[24:25] offset:512
	global_atomic_add_f32 v145, v161, s[24:25] offset:512
	v_add_u32_e32 v138, 0x10000, v134
	v_add_u32_e32 v139, 0x12000, v134
	v_add_u32_e32 v140, 0x14000, v134
	v_add_u32_e32 v141, 0x16000, v134
	v_add_u32_e32 v142, 0x18000, v134
	v_add_u32_e32 v143, 0x1a000, v134
	v_add_u32_e32 v144, 0x1c000, v134
	v_add_u32_e32 v145, 0x1e000, v134
	v_pk_mul_f32 v[118:119], v[118:119], 0.5 op_sel_hi:[1,0]
	v_pk_mul_f32 v[120:121], v[120:121], 0.5 op_sel_hi:[1,0]
	v_pk_mul_f32 v[110:111], v[110:111], 0.5 op_sel_hi:[1,0]
	v_pk_mul_f32 v[112:113], v[112:113], 0.5 op_sel_hi:[1,0]
	ds_write_b128 v136, v[118:121]
	ds_write_b128 v136, v[110:113] offset:64
	ds_read_b32 v146, v137
	ds_read_b32 v147, v137 offset:288
	ds_read_b32 v148, v137 offset:576
	ds_read_b32 v149, v137 offset:864
	ds_read_b32 v150, v137 offset:1152
	ds_read_b32 v151, v137 offset:1440
	ds_read_b32 v152, v137 offset:1728
	ds_read_b32 v153, v137 offset:2016
	s_waitcnt lgkmcnt(0)
	global_atomic_add_f32 v138, v146, s[24:25]
	global_atomic_add_f32 v139, v147, s[24:25]
	global_atomic_add_f32 v140, v148, s[24:25]
	global_atomic_add_f32 v141, v149, s[24:25]
	global_atomic_add_f32 v142, v150, s[24:25]
	global_atomic_add_f32 v143, v151, s[24:25]
	global_atomic_add_f32 v144, v152, s[24:25]
	global_atomic_add_f32 v145, v153, s[24:25]
	v_pk_mul_f32 v[98:99], v[98:99], 0.5 op_sel_hi:[1,0]
	v_pk_mul_f32 v[100:101], v[100:101], 0.5 op_sel_hi:[1,0]
	v_pk_mul_f32 v[90:91], v[90:91], 0.5 op_sel_hi:[1,0]
	v_pk_mul_f32 v[92:93], v[92:93], 0.5 op_sel_hi:[1,0]
	ds_write_b128 v136, v[98:101]
	ds_write_b128 v136, v[90:93] offset:64
	ds_read_b32 v154, v137
	ds_read_b32 v155, v137 offset:288
	ds_read_b32 v156, v137 offset:576
	ds_read_b32 v157, v137 offset:864
	ds_read_b32 v158, v137 offset:1152
	ds_read_b32 v159, v137 offset:1440
	ds_read_b32 v160, v137 offset:1728
	ds_read_b32 v161, v137 offset:2016
	s_waitcnt lgkmcnt(0)
	global_atomic_add_f32 v138, v154, s[24:25] offset:512
	global_atomic_add_f32 v139, v155, s[24:25] offset:512
	global_atomic_add_f32 v140, v156, s[24:25] offset:512
	global_atomic_add_f32 v141, v157, s[24:25] offset:512
	global_atomic_add_f32 v142, v158, s[24:25] offset:512
	global_atomic_add_f32 v143, v159, s[24:25] offset:512
	global_atomic_add_f32 v144, v160, s[24:25] offset:512
	global_atomic_add_f32 v145, v161, s[24:25] offset:512
.Lg2s_q1:
	s_cmp_lg_u32 s5, 1
	s_cbranch_scc1 .Lg2s_q2
	v_add_u32_e32 v138, 0x20000, v134
	v_add_u32_e32 v139, 0x22000, v134
	v_add_u32_e32 v140, 0x24000, v134
	v_add_u32_e32 v141, 0x26000, v134
	v_add_u32_e32 v142, 0x28000, v134
	v_add_u32_e32 v143, 0x2a000, v134
	v_add_u32_e32 v144, 0x2c000, v134
	v_add_u32_e32 v145, 0x2e000, v134
	v_pk_mul_f32 v[102:103], v[102:103], 0.5 op_sel_hi:[1,0]
	v_pk_mul_f32 v[104:105], v[104:105], 0.5 op_sel_hi:[1,0]
	v_pk_mul_f32 v[94:95], v[94:95], 0.5 op_sel_hi:[1,0]
	v_pk_mul_f32 v[96:97], v[96:97], 0.5 op_sel_hi:[1,0]
	ds_write_b128 v136, v[102:105]
	ds_write_b128 v136, v[94:97] offset:64
	ds_read_b32 v146, v137
	ds_read_b32 v147, v137 offset:288
	ds_read_b32 v148, v137 offset:576
	ds_read_b32 v149, v137 offset:864
	ds_read_b32 v150, v137 offset:1152
	ds_read_b32 v151, v137 offset:1440
	ds_read_b32 v152, v137 offset:1728
	ds_read_b32 v153, v137 offset:2016
	s_waitcnt lgkmcnt(0)
	global_atomic_add_f32 v138, v146, s[24:25]
	global_atomic_add_f32 v139, v147, s[24:25]
	global_atomic_add_f32 v140, v148, s[24:25]
	global_atomic_add_f32 v141, v149, s[24:25]
	global_atomic_add_f32 v142, v150, s[24:25]
	global_atomic_add_f32 v143, v151, s[24:25]
	global_atomic_add_f32 v144, v152, s[24:25]
	global_atomic_add_f32 v145, v153, s[24:25]
	v_pk_mul_f32 v[82:83], v[82:83], 0.5 op_sel_hi:[1,0]
	v_pk_mul_f32 v[84:85], v[84:85], 0.5 op_sel_hi:[1,0]
	v_pk_mul_f32 v[74:75], v[74:75], 0.5 op_sel_hi:[1,0]
	v_pk_mul_f32 v[76:77], v[76:77], 0.5 op_sel_hi:[1,0]
	ds_write_b128 v136, v[82:85]
	ds_write_b128 v136, v[74:77] offset:64
	ds_read_b32 v154, v137
	ds_read_b32 v155, v137 offset:288
	ds_read_b32 v156, v137 offset:576
	ds_read_b32 v157, v137 offset:864
	ds_read_b32 v158, v137 offset:1152
	ds_read_b32 v159, v137 offset:1440
	ds_read_b32 v160, v137 offset:1728
	ds_read_b32 v161, v137 offset:2016
	s_waitcnt lgkmcnt(0)
	global_atomic_add_f32 v138, v154, s[24:25] offset:512
	global_atomic_add_f32 v139, v155, s[24:25] offset:512
	global_atomic_add_f32 v140, v156, s[24:25] offset:512
	global_atomic_add_f32 v141, v157, s[24:25] offset:512
	global_atomic_add_f32 v142, v158, s[24:25] offset:512
	global_atomic_add_f32 v143, v159, s[24:25] offset:512
	global_atomic_add_f32 v144, v160, s[24:25] offset:512
	global_atomic_add_f32 v145, v161, s[24:25] offset:512
	v_add_u32_e32 v138, 0x30000, v134
	v_add_u32_e32 v139, 0x32000, v134
	v_add_u32_e32 v140, 0x34000, v134
	v_add_u32_e32 v141, 0x36000, v134
	v_add_u32_e32 v142, 0x38000, v134
	v_add_u32_e32 v143, 0x3a000, v134
	v_add_u32_e32 v144, 0x3c000, v134
	v_add_u32_e32 v145, 0x3e000, v134
	v_pk_mul_f32 v[86:87], v[86:87], 0.5 op_sel_hi:[1,0]
	v_pk_mul_f32 v[88:89], v[88:89], 0.5 op_sel_hi:[1,0]
	v_pk_mul_f32 v[78:79], v[78:79], 0.5 op_sel_hi:[1,0]
	v_pk_mul_f32 v[80:81], v[80:81], 0.5 op_sel_hi:[1,0]
	ds_write_b128 v136, v[86:89]
	ds_write_b128 v136, v[78:81] offset:64
	ds_read_b32 v146, v137
	ds_read_b32 v147, v137 offset:288
	ds_read_b32 v148, v137 offset:576
	ds_read_b32 v149, v137 offset:864
	ds_read_b32 v150, v137 offset:1152
	ds_read_b32 v151, v137 offset:1440
	ds_read_b32 v152, v137 offset:1728
	ds_read_b32 v153, v137 offset:2016
	s_waitcnt lgkmcnt(0)
	global_atomic_add_f32 v138, v146, s[24:25]
	global_atomic_add_f32 v139, v147, s[24:25]
	global_atomic_add_f32 v140, v148, s[24:25]
	global_atomic_add_f32 v141, v149, s[24:25]
	global_atomic_add_f32 v142, v150, s[24:25]
	global_atomic_add_f32 v143, v151, s[24:25]
	global_atomic_add_f32 v144, v152, s[24:25]
	global_atomic_add_f32 v145, v153, s[24:25]
	v_pk_mul_f32 v[70:71], v[70:71], 0.5 op_sel_hi:[1,0]
	v_pk_mul_f32 v[72:73], v[72:73], 0.5 op_sel_hi:[1,0]
	v_pk_mul_f32 v[66:67], v[66:67], 0.5 op_sel_hi:[1,0]
	v_pk_mul_f32 v[68:69], v[68:69], 0.5 op_sel_hi:[1,0]
	ds_write_b128 v136, v[70:73]
	ds_write_b128 v136, v[66:69] offset:64
	ds_read_b32 v154, v137
	ds_read_b32 v155, v137 offset:288
	ds_read_b32 v156, v137 offset:576
	ds_read_b32 v157, v137 offset:864
	ds_read_b32 v158, v137 offset:1152
	ds_read_b32 v159, v137 offset:1440
	ds_read_b32 v160, v137 offset:1728
	ds_read_b32 v161, v137 offset:2016
	s_waitcnt lgkmcnt(0)
	global_atomic_add_f32 v138, v154, s[24:25] offset:512
	global_atomic_add_f32 v139, v155, s[24:25] offset:512
	global_atomic_add_f32 v140, v156, s[24:25] offset:512
	global_atomic_add_f32 v141, v157, s[24:25] offset:512
	global_atomic_add_f32 v142, v158, s[24:25] offset:512
	global_atomic_add_f32 v143, v159, s[24:25] offset:512
	global_atomic_add_f32 v144, v160, s[24:25] offset:512
	global_atomic_add_f32 v145, v161, s[24:25] offset:512
.Lg2s_q2:
	s_cmp_lg_u32 s5, 2
	s_cbranch_scc1 .Lg2s_q3
	v_add_u32_e32 v138, 0x80000, v134
	v_add_u32_e32 v139, 0x82000, v134
	v_add_u32_e32 v140, 0x84000, v134
	v_add_u32_e32 v141, 0x86000, v134
	v_add_u32_e32 v142, 0x88000, v134
	v_add_u32_e32 v143, 0x8a000, v134
	v_add_u32_e32 v144, 0x8c000, v134
	v_add_u32_e32 v145, 0x8e000, v134
	v_pk_mul_f32 v[62:63], v[62:63], 0.5 op_sel_hi:[1,0]
	v_pk_mul_f32 v[64:65], v[64:65], 0.5 op_sel_hi:[1,0]
	v_pk_mul_f32 v[58:59], v[58:59], 0.5 op_sel_hi:[1,0]
	v_pk_mul_f32 v[60:61], v[60:61], 0.5 op_sel_hi:[1,0]
	ds_write_b128 v136, v[62:65]
	ds_write_b128 v136, v[58:61] offset:64
	ds_read_b32 v146, v137
	ds_read_b32 v147, v137 offset:288
	ds_read_b32 v148, v137 offset:576
	ds_read_b32 v149, v137 offset:864
	ds_read_b32 v150, v137 offset:1152
	ds_read_b32 v151, v137 offset:1440
	ds_read_b32 v152, v137 offset:1728
	ds_read_b32 v153, v137 offset:2016
	s_waitcnt lgkmcnt(0)
	global_atomic_add_f32 v138, v146, s[24:25]
	global_atomic_add_f32 v139, v147, s[24:25]
	global_atomic_add_f32 v140, v148, s[24:25]
	global_atomic_add_f32 v141, v149, s[24:25]
	global_atomic_add_f32 v142, v150, s[24:25]
	global_atomic_add_f32 v143, v151, s[24:25]
	global_atomic_add_f32 v144, v152, s[24:25]
	global_atomic_add_f32 v145, v153, s[24:25]
	v_pk_mul_f32 v[50:51], v[50:51], 0.5 op_sel_hi:[1,0]
	v_pk_mul_f32 v[52:53], v[52:53], 0.5 op_sel_hi:[1,0]
	v_pk_mul_f32 v[42:43], v[42:43], 0.5 op_sel_hi:[1,0]
	v_pk_mul_f32 v[44:45], v[44:45], 0.5 op_sel_hi:[1,0]
	ds_write_b128 v136, v[50:53]
	ds_write_b128 v136, v[42:45] offset:64
	ds_read_b32 v154, v137
	ds_read_b32 v155, v137 offset:288
	ds_read_b32 v156, v137 offset:576
	ds_read_b32 v157, v137 offset:864
	ds_read_b32 v158, v137 offset:1152
	ds_read_b32 v159, v137 offset:1440
	ds_read_b32 v160, v137 offset:1728
	ds_read_b32 v161, v137 offset:2016
	s_waitcnt lgkmcnt(0)
	global_atomic_add_f32 v138, v154, s[24:25] offset:512
	global_atomic_add_f32 v139, v155, s[24:25] offset:512
	global_atomic_add_f32 v140, v156, s[24:25] offset:512
	global_atomic_add_f32 v141, v157, s[24:25] offset:512
	global_atomic_add_f32 v142, v158, s[24:25] offset:512
	global_atomic_add_f32 v143, v159, s[24:25] offset:512
	global_atomic_add_f32 v144, v160, s[24:25] offset:512
	global_atomic_add_f32 v145, v161, s[24:25] offset:512
	v_add_u32_e32 v138, 0x90000, v134
	v_add_u32_e32 v139, 0x92000, v134
	v_add_u32_e32 v140, 0x94000, v134
	v_add_u32_e32 v141, 0x96000, v134
	v_add_u32_e32 v142, 0x98000, v134
	v_add_u32_e32 v143, 0x9a000, v134
	v_add_u32_e32 v144, 0x9c000, v134
	v_add_u32_e32 v145, 0x9e000, v134
	v_pk_mul_f32 v[54:55], v[54:55], 0.5 op_sel_hi:[1,0]
	v_pk_mul_f32 v[56:57], v[56:57], 0.5 op_sel_hi:[1,0]
	v_pk_mul_f32 v[46:47], v[46:47], 0.5 op_sel_hi:[1,0]
	v_pk_mul_f32 v[48:49], v[48:49], 0.5 op_sel_hi:[1,0]
	ds_write_b128 v136, v[54:57]
	ds_write_b128 v136, v[46:49] offset:64
	ds_read_b32 v146, v137
	ds_read_b32 v147, v137 offset:288
	ds_read_b32 v148, v137 offset:576
	ds_read_b32 v149, v137 offset:864
	ds_read_b32 v150, v137 offset:1152
	ds_read_b32 v151, v137 offset:1440
	ds_read_b32 v152, v137 offset:1728
	ds_read_b32 v153, v137 offset:2016
	s_waitcnt lgkmcnt(0)
	global_atomic_add_f32 v138, v146, s[24:25]
	global_atomic_add_f32 v139, v147, s[24:25]
	global_atomic_add_f32 v140, v148, s[24:25]
	global_atomic_add_f32 v141, v149, s[24:25]
	global_atomic_add_f32 v142, v150, s[24:25]
	global_atomic_add_f32 v143, v151, s[24:25]
	global_atomic_add_f32 v144, v152, s[24:25]
	global_atomic_add_f32 v145, v153, s[24:25]
	v_pk_mul_f32 v[34:35], v[34:35], 0.5 op_sel_hi:[1,0]
	v_pk_mul_f32 v[36:37], v[36:37], 0.5 op_sel_hi:[1,0]
	v_pk_mul_f32 v[26:27], v[26:27], 0.5 op_sel_hi:[1,0]
	v_pk_mul_f32 v[28:29], v[28:29], 0.5 op_sel_hi:[1,0]
	ds_write_b128 v136, v[34:37]
	ds_write_b128 v136, v[26:29] offset:64
	ds_read_b32 v154, v137
	ds_read_b32 v155, v137 offset:288
	ds_read_b32 v156, v137 offset:576
	ds_read_b32 v157, v137 offset:864
	ds_read_b32 v158, v137 offset:1152
	ds_read_b32 v159, v137 offset:1440
	ds_read_b32 v160, v137 offset:1728
	ds_read_b32 v161, v137 offset:2016
	s_waitcnt lgkmcnt(0)
	global_atomic_add_f32 v138, v154, s[24:25] offset:512
	global_atomic_add_f32 v139, v155, s[24:25] offset:512
	global_atomic_add_f32 v140, v156, s[24:25] offset:512
	global_atomic_add_f32 v141, v157, s[24:25] offset:512
	global_atomic_add_f32 v142, v158, s[24:25] offset:512
	global_atomic_add_f32 v143, v159, s[24:25] offset:512
	global_atomic_add_f32 v144, v160, s[24:25] offset:512
	global_atomic_add_f32 v145, v161, s[24:25] offset:512
.Lg2s_q3:
	s_cmp_lg_u32 s5, 3
	s_cbranch_scc1 .Lg2s_q4
	v_add_u32_e32 v138, 0xa0000, v134
	v_add_u32_e32 v139, 0xa2000, v134
	v_add_u32_e32 v140, 0xa4000, v134
	v_add_u32_e32 v141, 0xa6000, v134
	v_add_u32_e32 v142, 0xa8000, v134
	v_add_u32_e32 v143, 0xaa000, v134
	v_add_u32_e32 v144, 0xac000, v134
	v_add_u32_e32 v145, 0xae000, v134
	v_pk_mul_f32 v[38:39], v[38:39], 0.5 op_sel_hi:[1,0]
	v_pk_mul_f32 v[40:41], v[40:41], 0.5 op_sel_hi:[1,0]
	v_pk_mul_f32 v[30:31], v[30:31], 0.5 op_sel_hi:[1,0]
	v_pk_mul_f32 v[32:33], v[32:33], 0.5 op_sel_hi:[1,0]
	ds_write_b128 v136, v[38:41]
	ds_write_b128 v136, v[30:33] offset:64
	ds_read_b32 v146, v137
	ds_read_b32 v147, v137 offset:288
	ds_read_b32 v148, v137 offset:576
	ds_read_b32 v149, v137 offset:864
	ds_read_b32 v150, v137 offset:1152
	ds_read_b32 v151, v137 offset:1440
	ds_read_b32 v152, v137 offset:1728
	ds_read_b32 v153, v137 offset:2016
	s_waitcnt lgkmcnt(0)
	global_atomic_add_f32 v138, v146, s[24:25]
	global_atomic_add_f32 v139, v147, s[24:25]
	global_atomic_add_f32 v140, v148, s[24:25]
	global_atomic_add_f32 v141, v149, s[24:25]
	global_atomic_add_f32 v142, v150, s[24:25]
	global_atomic_add_f32 v143, v151, s[24:25]
	global_atomic_add_f32 v144, v152, s[24:25]
	global_atomic_add_f32 v145, v153, s[24:25]
	v_pk_mul_f32 v[18:19], v[18:19], 0.5 op_sel_hi:[1,0]
	v_pk_mul_f32 v[20:21], v[20:21], 0.5 op_sel_hi:[1,0]
	v_pk_mul_f32 v[10:11], v[10:11], 0.5 op_sel_hi:[1,0]
	v_pk_mul_f32 v[12:13], v[12:13], 0.5 op_sel_hi:[1,0]
	ds_write_b128 v136, v[18:21]
	ds_write_b128 v136, v[10:13] offset:64
	ds_read_b32 v154, v137
	ds_read_b32 v155, v137 offset:288
	ds_read_b32 v156, v137 offset:576
	ds_read_b32 v157, v137 offset:864
	ds_read_b32 v158, v137 offset:1152
	ds_read_b32 v159, v137 offset:1440
	ds_read_b32 v160, v137 offset:1728
	ds_read_b32 v161, v137 offset:2016
	s_waitcnt lgkmcnt(0)
	global_atomic_add_f32 v138, v154, s[24:25] offset:512
	global_atomic_add_f32 v139, v155, s[24:25] offset:512
	global_atomic_add_f32 v140, v156, s[24:25] offset:512
	global_atomic_add_f32 v141, v157, s[24:25] offset:512
	global_atomic_add_f32 v142, v158, s[24:25] offset:512
	global_atomic_add_f32 v143, v159, s[24:25] offset:512
	global_atomic_add_f32 v144, v160, s[24:25] offset:512
	global_atomic_add_f32 v145, v161, s[24:25] offset:512
	v_add_u32_e32 v138, 0xb0000, v134
	v_add_u32_e32 v139, 0xb2000, v134
	v_add_u32_e32 v140, 0xb4000, v134
	v_add_u32_e32 v141, 0xb6000, v134
	v_add_u32_e32 v142, 0xb8000, v134
	v_add_u32_e32 v143, 0xba000, v134
	v_add_u32_e32 v144, 0xbc000, v134
	v_add_u32_e32 v145, 0xbe000, v134
	v_pk_mul_f32 v[22:23], v[22:23], 0.5 op_sel_hi:[1,0]
	v_pk_mul_f32 v[24:25], v[24:25], 0.5 op_sel_hi:[1,0]
	v_pk_mul_f32 v[14:15], v[14:15], 0.5 op_sel_hi:[1,0]
	v_pk_mul_f32 v[16:17], v[16:17], 0.5 op_sel_hi:[1,0]
	ds_write_b128 v136, v[22:25]
	ds_write_b128 v136, v[14:17] offset:64
	ds_read_b32 v146, v137
	ds_read_b32 v147, v137 offset:288
	ds_read_b32 v148, v137 offset:576
	ds_read_b32 v149, v137 offset:864
	ds_read_b32 v150, v137 offset:1152
	ds_read_b32 v151, v137 offset:1440
	ds_read_b32 v152, v137 offset:1728
	ds_read_b32 v153, v137 offset:2016
	s_waitcnt lgkmcnt(0)
	global_atomic_add_f32 v138, v146, s[24:25]
	global_atomic_add_f32 v139, v147, s[24:25]
	global_atomic_add_f32 v140, v148, s[24:25]
	global_atomic_add_f32 v141, v149, s[24:25]
	global_atomic_add_f32 v142, v150, s[24:25]
	global_atomic_add_f32 v143, v151, s[24:25]
	global_atomic_add_f32 v144, v152, s[24:25]
	global_atomic_add_f32 v145, v153, s[24:25]
	v_pk_mul_f32 v[6:7], v[6:7], 0.5 op_sel_hi:[1,0]
	v_pk_mul_f32 v[8:9], v[8:9], 0.5 op_sel_hi:[1,0]
	v_pk_mul_f32 v[2:3], v[2:3], 0.5 op_sel_hi:[1,0]
	v_pk_mul_f32 v[4:5], v[4:5], 0.5 op_sel_hi:[1,0]
	ds_write_b128 v136, v[6:9]
	ds_write_b128 v136, v[2:5] offset:64
	ds_read_b32 v154, v137
	ds_read_b32 v155, v137 offset:288
	ds_read_b32 v156, v137 offset:576
	ds_read_b32 v157, v137 offset:864
	ds_read_b32 v158, v137 offset:1152
	ds_read_b32 v159, v137 offset:1440
	ds_read_b32 v160, v137 offset:1728
	ds_read_b32 v161, v137 offset:2016
	s_waitcnt lgkmcnt(0)
	global_atomic_add_f32 v138, v154, s[24:25] offset:512
	global_atomic_add_f32 v139, v155, s[24:25] offset:512
	global_atomic_add_f32 v140, v156, s[24:25] offset:512
	global_atomic_add_f32 v141, v157, s[24:25] offset:512
	global_atomic_add_f32 v142, v158, s[24:25] offset:512
	global_atomic_add_f32 v143, v159, s[24:25] offset:512
	global_atomic_add_f32 v144, v160, s[24:25] offset:512
	global_atomic_add_f32 v145, v161, s[24:25] offset:512

.LBB0_1549:
	s_add_i32 s10, s44, 0x100
	s_and_b64 s[8:9], s[42:43], exec
	s_cselect_b32 s9, 0, s10
	s_cselect_b32 s8, 0, 0
	s_add_u32 s46, s72, s9
	s_addc_u32 s47, s73, s8
	s_add_i32 s10, 0, 0x10000
	s_add_u32 s48, s38, s9
	s_addc_u32 s49, s39, s8
	s_add_i32 s8, 0, 0x14000
	s_add_u32 s52, s68, s44
	s_addc_u32 s53, s69, 0
	s_add_i32 s67, s10, s54
	s_add_i32 m0, s4, 0xc000
	s_add_i32 s9, s4, 0xe000
	s_add_i32 s64, s67, 0x2000
	s_add_u32 s50, s48, 0x40000
	s_addc_u32 s51, s49, 0
	s_add_i32 s66, s8, s54
	v_add_u32_e32 v148, s10, v134
	v_add_u32_e32 v164, s8, v134
	s_add_i32 s65, s66, 0x2000
	s_add_i32 s63, 0, 0x18000
	s_add_i32 s62, 0, 0x1c000
	ds_read_b128 v[136:139], v148
	ds_read_b128 v[140:143], v148 offset:1024
	ds_read_b128 v[144:147], v148 offset:2048
	ds_read_b128 v[148:151], v148 offset:3072
	ds_read_b128 v[152:155], v164
	ds_read_b128 v[156:159], v164 offset:1024
	ds_read_b128 v[160:163], v164 offset:2048
	ds_read_b128 v[164:167], v164 offset:3072
	s_add_u32 s44, s46, 0x40000
	s_addc_u32 s45, s47, 0
	s_add_i32 s61, s63, s54
	s_add_i32 s60, s61, 0x2000
	s_add_u32 s42, s48, 0x40080
	s_addc_u32 s43, s49, 0
	s_add_i32 s69, s62, s54
	s_add_i32 s68, s69, 0x2000
	v_lshl_add_u64 v[202:203], s[52:53], 0, v[0:1]
	v_lshl_add_u64 v[202:203], v[202:203], 0, s[26:27]
	ds_read_b128 v[168:171], v135
	ds_read_b128 v[172:175], v135 offset:1024
	ds_read_b128 v[176:179], v135 offset:2048
	ds_read_b128 v[180:183], v135 offset:3072
	ds_read_b128 v[184:187], v135 offset:4096
	ds_read_b128 v[224:227], v135 offset:5120
	ds_read_b128 v[228:231], v135 offset:6144
	ds_read_b128 v[232:235], v135 offset:7168
	global_load_lds_dwordx4 v[202:203], off
	v_lshl_add_u64 v[202:203], s[52:53], 0, v[130:131]
	v_lshl_add_u64 v[202:203], v[202:203], 0, s[26:27]
	s_mov_b32 m0, s9
	s_nop 0
	global_load_lds_dwordx4 v[202:203], off
	s_waitcnt vmcnt(8)
	s_waitcnt lgkmcnt(0)
	s_barrier
	s_setprio 1
	s_waitcnt lgkmcnt(0)
	v_mfma_f32_16x16x32_bf16 v[126:129], v[136:139], v[168:171], v[126:129]
	v_mfma_f32_16x16x32_bf16 v[122:125], v[144:147], v[168:171], v[122:125]
	v_mfma_f32_16x16x32_bf16 v[118:121], v[136:139], v[176:179], v[118:121]
	v_mfma_f32_16x16x32_bf16 v[114:117], v[144:147], v[176:179], v[114:117]
	v_mfma_f32_16x16x32_bf16 v[102:105], v[136:139], v[184:187], v[102:105]
	v_mfma_f32_16x16x32_bf16 v[98:101], v[144:147], v[184:187], v[98:101]
	v_mfma_f32_16x16x32_bf16 v[86:89], v[136:139], v[228:231], v[86:89]
	v_mfma_f32_16x16x32_bf16 v[82:85], v[144:147], v[228:231], v[82:85]
	v_mfma_f32_16x16x32_bf16 v[126:129], v[140:143], v[172:175], v[126:129]
	v_mfma_f32_16x16x32_bf16 v[122:125], v[148:151], v[172:175], v[122:125]
	v_mfma_f32_16x16x32_bf16 v[118:121], v[140:143], v[180:183], v[118:121]
	v_mfma_f32_16x16x32_bf16 v[114:117], v[148:151], v[180:183], v[114:117]
	v_mfma_f32_16x16x32_bf16 v[102:105], v[140:143], v[224:227], v[102:105]
	v_mfma_f32_16x16x32_bf16 v[98:101], v[148:151], v[224:227], v[98:101]
	v_mfma_f32_16x16x32_bf16 v[86:89], v[140:143], v[232:235], v[86:89]
	v_mfma_f32_16x16x32_bf16 v[82:85], v[148:151], v[232:235], v[82:85]
	s_setprio 0
	s_setprio 1
	v_mfma_f32_16x16x32_bf16 v[110:113], v[152:155], v[168:171], v[110:113]
	v_mfma_f32_16x16x32_bf16 v[106:109], v[160:163], v[168:171], v[106:109]
	v_mfma_f32_16x16x32_bf16 v[94:97], v[152:155], v[176:179], v[94:97]
	v_mfma_f32_16x16x32_bf16 v[90:93], v[160:163], v[176:179], v[90:93]
	v_mfma_f32_16x16x32_bf16 v[78:81], v[152:155], v[184:187], v[78:81]
	v_mfma_f32_16x16x32_bf16 v[74:77], v[160:163], v[184:187], v[74:77]
	v_mfma_f32_16x16x32_bf16 v[70:73], v[152:155], v[228:231], v[70:73]
	v_mfma_f32_16x16x32_bf16 v[66:69], v[160:163], v[228:231], v[66:69]
	v_mfma_f32_16x16x32_bf16 v[110:113], v[156:159], v[172:175], v[110:113]
	v_mfma_f32_16x16x32_bf16 v[106:109], v[164:167], v[172:175], v[106:109]
	v_mfma_f32_16x16x32_bf16 v[94:97], v[156:159], v[180:183], v[94:97]
	v_mfma_f32_16x16x32_bf16 v[90:93], v[164:167], v[180:183], v[90:93]
	v_mfma_f32_16x16x32_bf16 v[78:81], v[156:159], v[224:227], v[78:81]
	v_mfma_f32_16x16x32_bf16 v[74:77], v[164:167], v[224:227], v[74:77]
	v_mfma_f32_16x16x32_bf16 v[70:73], v[156:159], v[232:235], v[70:73]
	v_mfma_f32_16x16x32_bf16 v[66:69], v[164:167], v[232:235], v[66:69]
	s_setprio 0
	s_barrier
	s_mov_b32 m0, s67
	v_lshl_add_u64 v[202:203], s[48:49], 0, v[0:1]
	ds_read_b128 v[168:171], v135 offset:16384
	ds_read_b128 v[172:175], v135 offset:17408
	ds_read_b128 v[176:179], v135 offset:18432
	ds_read_b128 v[180:183], v135 offset:19456
	ds_read_b128 v[184:187], v135 offset:20480
	ds_read_b128 v[224:227], v135 offset:21504
	ds_read_b128 v[228:231], v135 offset:22528
	ds_read_b128 v[232:235], v135 offset:23552
	global_load_lds_dwordx4 v[202:203], off
	v_lshl_add_u64 v[208:209], s[48:49], 0, v[130:131]
	s_mov_b32 m0, s64
	v_lshl_add_u64 v[236:237], s[50:51], 0, v[0:1]
	global_load_lds_dwordx4 v[208:209], off
	s_mov_b32 m0, s66
	v_lshl_add_u64 v[238:239], s[46:47], 0, v[130:131]
	global_load_lds_dwordx4 v[236:237], off
	v_lshl_add_u64 v[236:237], s[50:51], 0, v[130:131]
	s_mov_b32 m0, s65
	s_nop 0
	global_load_lds_dwordx4 v[236:237], off
	v_lshl_add_u64 v[236:237], s[46:47], 0, v[0:1]
	s_mov_b32 m0, s4
	s_nop 0
	global_load_lds_dwordx4 v[236:237], off
	s_mov_b32 m0, s5
	s_nop 0
	global_load_lds_dwordx4 v[238:239], off
	s_waitcnt vmcnt(8)
	s_waitcnt lgkmcnt(0)
	s_barrier
	s_setprio 1
	s_waitcnt lgkmcnt(0)
	v_mfma_f32_16x16x32_bf16 v[62:65], v[136:139], v[168:171], v[62:65]
	v_mfma_f32_16x16x32_bf16 v[58:61], v[144:147], v[168:171], v[58:61]
	v_mfma_f32_16x16x32_bf16 v[54:57], v[136:139], v[176:179], v[54:57]
	v_mfma_f32_16x16x32_bf16 v[50:53], v[144:147], v[176:179], v[50:53]
	v_mfma_f32_16x16x32_bf16 v[38:41], v[136:139], v[184:187], v[38:41]
	v_mfma_f32_16x16x32_bf16 v[34:37], v[144:147], v[184:187], v[34:37]
	v_mfma_f32_16x16x32_bf16 v[22:25], v[136:139], v[228:231], v[22:25]
	v_mfma_f32_16x16x32_bf16 v[18:21], v[144:147], v[228:231], v[18:21]
	v_mfma_f32_16x16x32_bf16 v[62:65], v[140:143], v[172:175], v[62:65]
	v_mfma_f32_16x16x32_bf16 v[58:61], v[148:151], v[172:175], v[58:61]
	v_mfma_f32_16x16x32_bf16 v[54:57], v[140:143], v[180:183], v[54:57]
	v_mfma_f32_16x16x32_bf16 v[50:53], v[148:151], v[180:183], v[50:53]
	v_mfma_f32_16x16x32_bf16 v[38:41], v[140:143], v[224:227], v[38:41]
	v_mfma_f32_16x16x32_bf16 v[34:37], v[148:151], v[224:227], v[34:37]
	v_mfma_f32_16x16x32_bf16 v[22:25], v[140:143], v[232:235], v[22:25]
	v_mfma_f32_16x16x32_bf16 v[18:21], v[148:151], v[232:235], v[18:21]
	s_setprio 0
	s_setprio 1
	v_mfma_f32_16x16x32_bf16 v[46:49], v[152:155], v[168:171], v[46:49]
	v_mfma_f32_16x16x32_bf16 v[42:45], v[160:163], v[168:171], v[42:45]
	v_mfma_f32_16x16x32_bf16 v[30:33], v[152:155], v[176:179], v[30:33]
	v_mfma_f32_16x16x32_bf16 v[26:29], v[160:163], v[176:179], v[26:29]
	v_mfma_f32_16x16x32_bf16 v[14:17], v[152:155], v[184:187], v[14:17]
	v_mfma_f32_16x16x32_bf16 v[10:13], v[160:163], v[184:187], v[10:13]
	v_mfma_f32_16x16x32_bf16 v[6:9], v[152:155], v[228:231], v[6:9]
	v_mfma_f32_16x16x32_bf16 v[2:5], v[160:163], v[228:231], v[2:5]
	v_mfma_f32_16x16x32_bf16 v[46:49], v[156:159], v[172:175], v[46:49]
	v_mfma_f32_16x16x32_bf16 v[42:45], v[164:167], v[172:175], v[42:45]
	v_mfma_f32_16x16x32_bf16 v[30:33], v[156:159], v[180:183], v[30:33]
	v_mfma_f32_16x16x32_bf16 v[26:29], v[164:167], v[180:183], v[26:29]
	v_mfma_f32_16x16x32_bf16 v[14:17], v[156:159], v[224:227], v[14:17]
	v_mfma_f32_16x16x32_bf16 v[10:13], v[164:167], v[224:227], v[10:13]
	v_mfma_f32_16x16x32_bf16 v[6:9], v[156:159], v[232:235], v[6:9]
	v_mfma_f32_16x16x32_bf16 v[2:5], v[164:167], v[232:235], v[2:5]
	s_setprio 0
	s_barrier
	v_add_u32_e32 v148, s63, v134
	v_add_u32_e32 v164, s62, v134
	ds_read_b128 v[136:139], v148
	ds_read_b128 v[140:143], v148 offset:1024
	ds_read_b128 v[144:147], v148 offset:2048
	ds_read_b128 v[148:151], v148 offset:3072
	ds_read_b128 v[152:155], v164
	ds_read_b128 v[156:159], v164 offset:1024
	ds_read_b128 v[160:163], v164 offset:2048
	ds_read_b128 v[164:167], v164 offset:3072
	s_mov_b32 m0, s55
	v_lshl_add_u64 v[240:241], s[44:45], 0, v[0:1]
	ds_read_b128 v[168:171], v135 offset:32768
	ds_read_b128 v[172:175], v135 offset:33792
	ds_read_b128 v[176:179], v135 offset:34816
	ds_read_b128 v[180:183], v135 offset:35840
	ds_read_b128 v[184:187], v135 offset:36864
	ds_read_b128 v[224:227], v135 offset:37888
	ds_read_b128 v[228:231], v135 offset:38912
	ds_read_b128 v[232:235], v135 offset:39936
	global_load_lds_dwordx4 v[240:241], off
	v_lshl_add_u64 v[240:241], s[44:45], 0, v[130:131]
	s_mov_b32 m0, s56
	s_nop 0
	global_load_lds_dwordx4 v[240:241], off
	s_waitcnt vmcnt(8)
	s_waitcnt lgkmcnt(0)
	s_barrier
	s_setprio 1
	s_waitcnt lgkmcnt(0)
	v_mfma_f32_16x16x32_bf16 v[126:129], v[136:139], v[168:171], v[126:129]
	v_mfma_f32_16x16x32_bf16 v[122:125], v[144:147], v[168:171], v[122:125]
	v_mfma_f32_16x16x32_bf16 v[118:121], v[136:139], v[176:179], v[118:121]
	v_mfma_f32_16x16x32_bf16 v[114:117], v[144:147], v[176:179], v[114:117]
	v_mfma_f32_16x16x32_bf16 v[102:105], v[136:139], v[184:187], v[102:105]
	v_mfma_f32_16x16x32_bf16 v[98:101], v[144:147], v[184:187], v[98:101]
	v_mfma_f32_16x16x32_bf16 v[86:89], v[136:139], v[228:231], v[86:89]
	v_mfma_f32_16x16x32_bf16 v[82:85], v[144:147], v[228:231], v[82:85]
	v_mfma_f32_16x16x32_bf16 v[126:129], v[140:143], v[172:175], v[126:129]
	v_mfma_f32_16x16x32_bf16 v[122:125], v[148:151], v[172:175], v[122:125]
	v_mfma_f32_16x16x32_bf16 v[118:121], v[140:143], v[180:183], v[118:121]
	v_mfma_f32_16x16x32_bf16 v[114:117], v[148:151], v[180:183], v[114:117]
	v_mfma_f32_16x16x32_bf16 v[102:105], v[140:143], v[224:227], v[102:105]
	v_mfma_f32_16x16x32_bf16 v[98:101], v[148:151], v[224:227], v[98:101]
	v_mfma_f32_16x16x32_bf16 v[86:89], v[140:143], v[232:235], v[86:89]
	v_mfma_f32_16x16x32_bf16 v[82:85], v[148:151], v[232:235], v[82:85]
	s_setprio 0
	s_setprio 1
	v_mfma_f32_16x16x32_bf16 v[110:113], v[152:155], v[168:171], v[110:113]
	v_mfma_f32_16x16x32_bf16 v[106:109], v[160:163], v[168:171], v[106:109]
	v_mfma_f32_16x16x32_bf16 v[94:97], v[152:155], v[176:179], v[94:97]
	v_mfma_f32_16x16x32_bf16 v[90:93], v[160:163], v[176:179], v[90:93]
	v_mfma_f32_16x16x32_bf16 v[78:81], v[152:155], v[184:187], v[78:81]
	v_mfma_f32_16x16x32_bf16 v[74:77], v[160:163], v[184:187], v[74:77]
	v_mfma_f32_16x16x32_bf16 v[70:73], v[152:155], v[228:231], v[70:73]
	v_mfma_f32_16x16x32_bf16 v[66:69], v[160:163], v[228:231], v[66:69]
	v_mfma_f32_16x16x32_bf16 v[110:113], v[156:159], v[172:175], v[110:113]
	v_mfma_f32_16x16x32_bf16 v[106:109], v[164:167], v[172:175], v[106:109]
	v_mfma_f32_16x16x32_bf16 v[94:97], v[156:159], v[180:183], v[94:97]
	v_mfma_f32_16x16x32_bf16 v[90:93], v[164:167], v[180:183], v[90:93]
	v_mfma_f32_16x16x32_bf16 v[78:81], v[156:159], v[224:227], v[78:81]
	v_mfma_f32_16x16x32_bf16 v[74:77], v[164:167], v[224:227], v[74:77]
	v_mfma_f32_16x16x32_bf16 v[70:73], v[156:159], v[232:235], v[70:73]
	v_mfma_f32_16x16x32_bf16 v[66:69], v[164:167], v[232:235], v[66:69]
	s_setprio 0
	s_barrier
	s_mov_b32 m0, s61
	v_lshl_add_u64 v[202:203], v[202:203], 0, s[26:27]
	ds_read_b128 v[168:171], v135 offset:49152
	ds_read_b128 v[172:175], v135 offset:50176
	ds_read_b128 v[176:179], v135 offset:51200
	ds_read_b128 v[180:183], v135 offset:52224
	ds_read_b128 v[184:187], v135 offset:53248
	ds_read_b128 v[224:227], v135 offset:54272
	ds_read_b128 v[228:231], v135 offset:55296
	ds_read_b128 v[232:235], v135 offset:56320
	global_load_lds_dwordx4 v[202:203], off
	v_lshl_add_u64 v[202:203], v[208:209], 0, s[26:27]
	s_mov_b32 m0, s60
	s_nop 0
	global_load_lds_dwordx4 v[202:203], off
	v_lshl_add_u64 v[202:203], s[42:43], 0, v[0:1]
	s_mov_b32 m0, s69
	s_nop 0
	global_load_lds_dwordx4 v[202:203], off
	v_lshl_add_u64 v[202:203], s[42:43], 0, v[130:131]
	s_mov_b32 m0, s68
	s_mov_b64 s[68:69], s[36:37]
	global_load_lds_dwordx4 v[202:203], off
	v_lshl_add_u64 v[202:203], v[236:237], 0, s[26:27]
	s_mov_b32 m0, s58
	s_nop 0
	global_load_lds_dwordx4 v[202:203], off
	v_lshl_add_u64 v[202:203], v[238:239], 0, s[26:27]
	s_mov_b32 m0, s59
	s_nop 0
	global_load_lds_dwordx4 v[202:203], off
	s_waitcnt vmcnt(8)
	s_waitcnt lgkmcnt(0)
	s_barrier
	s_setprio 1
	s_waitcnt lgkmcnt(0)
	v_mfma_f32_16x16x32_bf16 v[62:65], v[136:139], v[168:171], v[62:65]
	v_mfma_f32_16x16x32_bf16 v[58:61], v[144:147], v[168:171], v[58:61]
	v_mfma_f32_16x16x32_bf16 v[54:57], v[136:139], v[176:179], v[54:57]
	v_mfma_f32_16x16x32_bf16 v[50:53], v[144:147], v[176:179], v[50:53]
	v_mfma_f32_16x16x32_bf16 v[38:41], v[136:139], v[184:187], v[38:41]
	v_mfma_f32_16x16x32_bf16 v[34:37], v[144:147], v[184:187], v[34:37]
	v_mfma_f32_16x16x32_bf16 v[22:25], v[136:139], v[228:231], v[22:25]
	v_mfma_f32_16x16x32_bf16 v[18:21], v[144:147], v[228:231], v[18:21]
	v_mfma_f32_16x16x32_bf16 v[62:65], v[140:143], v[172:175], v[62:65]
	v_mfma_f32_16x16x32_bf16 v[58:61], v[148:151], v[172:175], v[58:61]
	v_mfma_f32_16x16x32_bf16 v[54:57], v[140:143], v[180:183], v[54:57]
	v_mfma_f32_16x16x32_bf16 v[50:53], v[148:151], v[180:183], v[50:53]
	v_mfma_f32_16x16x32_bf16 v[38:41], v[140:143], v[224:227], v[38:41]
	v_mfma_f32_16x16x32_bf16 v[34:37], v[148:151], v[224:227], v[34:37]
	v_mfma_f32_16x16x32_bf16 v[22:25], v[140:143], v[232:235], v[22:25]
	v_mfma_f32_16x16x32_bf16 v[18:21], v[148:151], v[232:235], v[18:21]
	s_setprio 0
	s_setprio 1
	v_mfma_f32_16x16x32_bf16 v[46:49], v[152:155], v[168:171], v[46:49]
	v_mfma_f32_16x16x32_bf16 v[42:45], v[160:163], v[168:171], v[42:45]
	v_mfma_f32_16x16x32_bf16 v[30:33], v[152:155], v[176:179], v[30:33]
	v_mfma_f32_16x16x32_bf16 v[26:29], v[160:163], v[176:179], v[26:29]
	v_mfma_f32_16x16x32_bf16 v[14:17], v[152:155], v[184:187], v[14:17]
	v_mfma_f32_16x16x32_bf16 v[10:13], v[160:163], v[184:187], v[10:13]
	v_mfma_f32_16x16x32_bf16 v[6:9], v[152:155], v[228:231], v[6:9]
	v_mfma_f32_16x16x32_bf16 v[2:5], v[160:163], v[228:231], v[2:5]
	v_mfma_f32_16x16x32_bf16 v[46:49], v[156:159], v[172:175], v[46:49]
	v_mfma_f32_16x16x32_bf16 v[42:45], v[164:167], v[172:175], v[42:45]
	v_mfma_f32_16x16x32_bf16 v[30:33], v[156:159], v[180:183], v[30:33]
	v_mfma_f32_16x16x32_bf16 v[26:29], v[164:167], v[180:183], v[26:29]
	v_mfma_f32_16x16x32_bf16 v[14:17], v[156:159], v[224:227], v[14:17]
	v_mfma_f32_16x16x32_bf16 v[10:13], v[164:167], v[224:227], v[10:13]
	v_mfma_f32_16x16x32_bf16 v[6:9], v[156:159], v[232:235], v[6:9]
	v_mfma_f32_16x16x32_bf16 v[2:5], v[164:167], v[232:235], v[2:5]
	s_setprio 0
	s_barrier
	s_andn2_b64 vcc, exec, s[40:41]
	s_mov_b64 s[42:43], -1
	s_mov_b64 s[40:41], 0
	s_movk_i32 s44, 0x100
	s_cbranch_vccz .LBB0_1549
	v_readlane_b32 s4, v254, 17
	s_lshr_b32 s5, s2, 4
	v_and_b32_e32 v0, 63, v204
	v_lshrrev_b32_e32 v130, 5, v0
	v_and_b32_e32 v131, 31, v0
	s_lshr_b32 vcc_lo, s28, 8
	s_lshl_b32 vcc_lo, vcc_lo, 6
	v_add_u32_e32 v134, vcc_lo, v130
	v_lshlrev_b32_e32 v134, 12, v134
	s_or_b32 vcc_hi, s4, s57
	v_or_b32_e32 v135, vcc_hi, v131
	v_lshl_add_u32 v134, v135, 2, v134
	v_add_u32_e32 v134, 0x8000000, v134
	s_lshr_b32 vcc_lo, s28, 6
	s_mul_i32 vcc_lo, vcc_lo, 0x900
	s_add_u32 vcc_lo, vcc_lo, 0x20200
	v_and_b32_e32 v136, 15, v132
	v_mul_u32_u24_e32 v136, 0x90, v136
	v_lshl_add_u32 v136, v133, 4, v136
	v_add_u32_e32 v136, vcc_lo, v136
	v_mul_u32_u24_e32 v137, 0x90, v130
	v_lshl_add_u32 v137, v131, 2, v137
	v_add_u32_e32 v137, vcc_lo, v137
	s_cmp_lg_u32 s5, 0
	s_cbranch_scc1 .Lg4s_q1
	v_mov_b32_e32 v138, v134
	v_add_u32_e32 v139, 0x2000, v134
	v_add_u32_e32 v140, 0x4000, v134
	v_add_u32_e32 v141, 0x6000, v134
	v_add_u32_e32 v142, 0x8000, v134
	v_add_u32_e32 v143, 0xa000, v134
	v_add_u32_e32 v144, 0xc000, v134
	v_add_u32_e32 v145, 0xe000, v134
	ds_write_b128 v136, v[126:129]
	ds_write_b128 v136, v[122:125] offset:64
	ds_read_b32 v146, v137
	ds_read_b32 v147, v137 offset:288
	ds_read_b32 v148, v137 offset:576
	ds_read_b32 v149, v137 offset:864
	ds_read_b32 v150, v137 offset:1152
	ds_read_b32 v151, v137 offset:1440
	ds_read_b32 v152, v137 offset:1728
	ds_read_b32 v153, v137 offset:2016
	s_waitcnt lgkmcnt(0)
	global_atomic_add_f32 v138, v146, s[24:25]
	global_atomic_add_f32 v139, v147, s[24:25]
	global_atomic_add_f32 v140, v148, s[24:25]
	global_atomic_add_f32 v141, v149, s[24:25]
	global_atomic_add_f32 v142, v150, s[24:25]
	global_atomic_add_f32 v143, v151, s[24:25]
	global_atomic_add_f32 v144, v152, s[24:25]
	global_atomic_add_f32 v145, v153, s[24:25]
	ds_write_b128 v136, v[110:113]
	ds_write_b128 v136, v[106:109] offset:64
	ds_read_b32 v154, v137
	ds_read_b32 v155, v137 offset:288
	ds_read_b32 v156, v137 offset:576
	ds_read_b32 v157, v137 offset:864
	ds_read_b32 v158, v137 offset:1152
	ds_read_b32 v159, v137 offset:1440
	ds_read_b32 v160, v137 offset:1728
	ds_read_b32 v161, v137 offset:2016
	s_waitcnt lgkmcnt(0)
	global_atomic_add_f32 v138, v154, s[24:25] offset:512
	global_atomic_add_f32 v139, v155, s[24:25] offset:512
	global_atomic_add_f32 v140, v156, s[24:25] offset:512
	global_atomic_add_f32 v141, v157, s[24:25] offset:512
	global_atomic_add_f32 v142, v158, s[24:25] offset:512
	global_atomic_add_f32 v143, v159, s[24:25] offset:512
	global_atomic_add_f32 v144, v160, s[24:25] offset:512
	global_atomic_add_f32 v145, v161, s[24:25] offset:512
.Lg4s_q1:
	s_cmp_lg_u32 s5, 1
	s_cbranch_scc1 .Lg4s_q2
	v_add_u32_e32 v138, 0x10000, v134
	v_add_u32_e32 v139, 0x12000, v134
	v_add_u32_e32 v140, 0x14000, v134
	v_add_u32_e32 v141, 0x16000, v134
	v_add_u32_e32 v142, 0x18000, v134
	v_add_u32_e32 v143, 0x1a000, v134
	v_add_u32_e32 v144, 0x1c000, v134
	v_add_u32_e32 v145, 0x1e000, v134
	ds_write_b128 v136, v[118:121]
	ds_write_b128 v136, v[114:117] offset:64
	ds_read_b32 v146, v137
	ds_read_b32 v147, v137 offset:288
	ds_read_b32 v148, v137 offset:576
	ds_read_b32 v149, v137 offset:864
	ds_read_b32 v150, v137 offset:1152
	ds_read_b32 v151, v137 offset:1440
	ds_read_b32 v152, v137 offset:1728
	ds_read_b32 v153, v137 offset:2016
	s_waitcnt lgkmcnt(0)
	global_atomic_add_f32 v138, v146, s[24:25]
	global_atomic_add_f32 v139, v147, s[24:25]
	global_atomic_add_f32 v140, v148, s[24:25]
	global_atomic_add_f32 v141, v149, s[24:25]
	global_atomic_add_f32 v142, v150, s[24:25]
	global_atomic_add_f32 v143, v151, s[24:25]
	global_atomic_add_f32 v144, v152, s[24:25]
	global_atomic_add_f32 v145, v153, s[24:25]
	ds_write_b128 v136, v[94:97]
	ds_write_b128 v136, v[90:93] offset:64
	ds_read_b32 v154, v137
	ds_read_b32 v155, v137 offset:288
	ds_read_b32 v156, v137 offset:576
	ds_read_b32 v157, v137 offset:864
	ds_read_b32 v158, v137 offset:1152
	ds_read_b32 v159, v137 offset:1440
	ds_read_b32 v160, v137 offset:1728
	ds_read_b32 v161, v137 offset:2016
	s_waitcnt lgkmcnt(0)
	global_atomic_add_f32 v138, v154, s[24:25] offset:512
	global_atomic_add_f32 v139, v155, s[24:25] offset:512
	global_atomic_add_f32 v140, v156, s[24:25] offset:512
	global_atomic_add_f32 v141, v157, s[24:25] offset:512
	global_atomic_add_f32 v142, v158, s[24:25] offset:512
	global_atomic_add_f32 v143, v159, s[24:25] offset:512
	global_atomic_add_f32 v144, v160, s[24:25] offset:512
	global_atomic_add_f32 v145, v161, s[24:25] offset:512
.Lg4s_q2:
	s_cmp_lg_u32 s5, 2
	s_cbranch_scc1 .Lg4s_q3
	v_add_u32_e32 v138, 0x20000, v134
	v_add_u32_e32 v139, 0x22000, v134
	v_add_u32_e32 v140, 0x24000, v134
	v_add_u32_e32 v141, 0x26000, v134
	v_add_u32_e32 v142, 0x28000, v134
	v_add_u32_e32 v143, 0x2a000, v134
	v_add_u32_e32 v144, 0x2c000, v134
	v_add_u32_e32 v145, 0x2e000, v134
	ds_write_b128 v136, v[102:105]
	ds_write_b128 v136, v[98:101] offset:64
	ds_read_b32 v146, v137
	ds_read_b32 v147, v137 offset:288
	ds_read_b32 v148, v137 offset:576
	ds_read_b32 v149, v137 offset:864
	ds_read_b32 v150, v137 offset:1152
	ds_read_b32 v151, v137 offset:1440
	ds_read_b32 v152, v137 offset:1728
	ds_read_b32 v153, v137 offset:2016
	s_waitcnt lgkmcnt(0)
	global_atomic_add_f32 v138, v146, s[24:25]
	global_atomic_add_f32 v139, v147, s[24:25]
	global_atomic_add_f32 v140, v148, s[24:25]
	global_atomic_add_f32 v141, v149, s[24:25]
	global_atomic_add_f32 v142, v150, s[24:25]
	global_atomic_add_f32 v143, v151, s[24:25]
	global_atomic_add_f32 v144, v152, s[24:25]
	global_atomic_add_f32 v145, v153, s[24:25]
	ds_write_b128 v136, v[78:81]
	ds_write_b128 v136, v[74:77] offset:64
	ds_read_b32 v154, v137
	ds_read_b32 v155, v137 offset:288
	ds_read_b32 v156, v137 offset:576
	ds_read_b32 v157, v137 offset:864
	ds_read_b32 v158, v137 offset:1152
	ds_read_b32 v159, v137 offset:1440
	ds_read_b32 v160, v137 offset:1728
	ds_read_b32 v161, v137 offset:2016
	s_waitcnt lgkmcnt(0)
	global_atomic_add_f32 v138, v154, s[24:25] offset:512
	global_atomic_add_f32 v139, v155, s[24:25] offset:512
	global_atomic_add_f32 v140, v156, s[24:25] offset:512
	global_atomic_add_f32 v141, v157, s[24:25] offset:512
	global_atomic_add_f32 v142, v158, s[24:25] offset:512
	global_atomic_add_f32 v143, v159, s[24:25] offset:512
	global_atomic_add_f32 v144, v160, s[24:25] offset:512
	global_atomic_add_f32 v145, v161, s[24:25] offset:512
.Lg4s_q3:
	s_cmp_lg_u32 s5, 3
	s_cbranch_scc1 .Lg4s_q4
	v_add_u32_e32 v138, 0x30000, v134
	v_add_u32_e32 v139, 0x32000, v134
	v_add_u32_e32 v140, 0x34000, v134
	v_add_u32_e32 v141, 0x36000, v134
	v_add_u32_e32 v142, 0x38000, v134
	v_add_u32_e32 v143, 0x3a000, v134
	v_add_u32_e32 v144, 0x3c000, v134
	v_add_u32_e32 v145, 0x3e000, v134
	ds_write_b128 v136, v[86:89]
	ds_write_b128 v136, v[82:85] offset:64
	ds_read_b32 v146, v137
	ds_read_b32 v147, v137 offset:288
	ds_read_b32 v148, v137 offset:576
	ds_read_b32 v149, v137 offset:864
	ds_read_b32 v150, v137 offset:1152
	ds_read_b32 v151, v137 offset:1440
	ds_read_b32 v152, v137 offset:1728
	ds_read_b32 v153, v137 offset:2016
	s_waitcnt lgkmcnt(0)
	global_atomic_add_f32 v138, v146, s[24:25]
	global_atomic_add_f32 v139, v147, s[24:25]
	global_atomic_add_f32 v140, v148, s[24:25]
	global_atomic_add_f32 v141, v149, s[24:25]
	global_atomic_add_f32 v142, v150, s[24:25]
	global_atomic_add_f32 v143, v151, s[24:25]
	global_atomic_add_f32 v144, v152, s[24:25]
	global_atomic_add_f32 v145, v153, s[24:25]
	ds_write_b128 v136, v[70:73]
	ds_write_b128 v136, v[66:69] offset:64
	ds_read_b32 v154, v137
	ds_read_b32 v155, v137 offset:288
	ds_read_b32 v156, v137 offset:576
	ds_read_b32 v157, v137 offset:864
	ds_read_b32 v158, v137 offset:1152
	ds_read_b32 v159, v137 offset:1440
	ds_read_b32 v160, v137 offset:1728
	ds_read_b32 v161, v137 offset:2016
	s_waitcnt lgkmcnt(0)
	global_atomic_add_f32 v138, v154, s[24:25] offset:512
	global_atomic_add_f32 v139, v155, s[24:25] offset:512
	global_atomic_add_f32 v140, v156, s[24:25] offset:512
	global_atomic_add_f32 v141, v157, s[24:25] offset:512
	global_atomic_add_f32 v142, v158, s[24:25] offset:512
	global_atomic_add_f32 v143, v159, s[24:25] offset:512
	global_atomic_add_f32 v144, v160, s[24:25] offset:512
	global_atomic_add_f32 v145, v161, s[24:25] offset:512
.Lg4s_q4:
	s_cmp_lg_u32 s5, 4
	s_cbranch_scc1 .Lg4s_q5
	v_add_u32_e32 v138, 0x80000, v134
	v_add_u32_e32 v139, 0x82000, v134
	v_add_u32_e32 v140, 0x84000, v134
	v_add_u32_e32 v141, 0x86000, v134
	v_add_u32_e32 v142, 0x88000, v134
	v_add_u32_e32 v143, 0x8a000, v134
	v_add_u32_e32 v144, 0x8c000, v134
	v_add_u32_e32 v145, 0x8e000, v134
	ds_write_b128 v136, v[62:65]
	ds_write_b128 v136, v[58:61] offset:64
	ds_read_b32 v146, v137
	ds_read_b32 v147, v137 offset:288
	ds_read_b32 v148, v137 offset:576
	ds_read_b32 v149, v137 offset:864
	ds_read_b32 v150, v137 offset:1152
	ds_read_b32 v151, v137 offset:1440
	ds_read_b32 v152, v137 offset:1728
	ds_read_b32 v153, v137 offset:2016
	s_waitcnt lgkmcnt(0)
	global_atomic_add_f32 v138, v146, s[24:25]
	global_atomic_add_f32 v139, v147, s[24:25]
	global_atomic_add_f32 v140, v148, s[24:25]
	global_atomic_add_f32 v141, v149, s[24:25]
	global_atomic_add_f32 v142, v150, s[24:25]
	global_atomic_add_f32 v143, v151, s[24:25]
	global_atomic_add_f32 v144, v152, s[24:25]
	global_atomic_add_f32 v145, v153, s[24:25]
	ds_write_b128 v136, v[46:49]
	ds_write_b128 v136, v[42:45] offset:64
	ds_read_b32 v154, v137
	ds_read_b32 v155, v137 offset:288
	ds_read_b32 v156, v137 offset:576
	ds_read_b32 v157, v137 offset:864
	ds_read_b32 v158, v137 offset:1152
	ds_read_b32 v159, v137 offset:1440
	ds_read_b32 v160, v137 offset:1728
	ds_read_b32 v161, v137 offset:2016
	s_waitcnt lgkmcnt(0)
	global_atomic_add_f32 v138, v154, s[24:25] offset:512
	global_atomic_add_f32 v139, v155, s[24:25] offset:512
	global_atomic_add_f32 v140, v156, s[24:25] offset:512
	global_atomic_add_f32 v141, v157, s[24:25] offset:512
	global_atomic_add_f32 v142, v158, s[24:25] offset:512
	global_atomic_add_f32 v143, v159, s[24:25] offset:512
	global_atomic_add_f32 v144, v160, s[24:25] offset:512
	global_atomic_add_f32 v145, v161, s[24:25] offset:512
.Lg4s_q5:
	s_cmp_lg_u32 s5, 5
	s_cbranch_scc1 .Lg4s_q6
	v_add_u32_e32 v138, 0x90000, v134
	v_add_u32_e32 v139, 0x92000, v134
	v_add_u32_e32 v140, 0x94000, v134
	v_add_u32_e32 v141, 0x96000, v134
	v_add_u32_e32 v142, 0x98000, v134
	v_add_u32_e32 v143, 0x9a000, v134
	v_add_u32_e32 v144, 0x9c000, v134
	v_add_u32_e32 v145, 0x9e000, v134
	ds_write_b128 v136, v[54:57]
	ds_write_b128 v136, v[50:53] offset:64
	ds_read_b32 v146, v137
	ds_read_b32 v147, v137 offset:288
	ds_read_b32 v148, v137 offset:576
	ds_read_b32 v149, v137 offset:864
	ds_read_b32 v150, v137 offset:1152
	ds_read_b32 v151, v137 offset:1440
	ds_read_b32 v152, v137 offset:1728
	ds_read_b32 v153, v137 offset:2016
	s_waitcnt lgkmcnt(0)
	global_atomic_add_f32 v138, v146, s[24:25]
	global_atomic_add_f32 v139, v147, s[24:25]
	global_atomic_add_f32 v140, v148, s[24:25]
	global_atomic_add_f32 v141, v149, s[24:25]
	global_atomic_add_f32 v142, v150, s[24:25]
	global_atomic_add_f32 v143, v151, s[24:25]
	global_atomic_add_f32 v144, v152, s[24:25]
	global_atomic_add_f32 v145, v153, s[24:25]
	ds_write_b128 v136, v[30:33]
	ds_write_b128 v136, v[26:29] offset:64
	ds_read_b32 v154, v137
	ds_read_b32 v155, v137 offset:288
	ds_read_b32 v156, v137 offset:576
	ds_read_b32 v157, v137 offset:864
	ds_read_b32 v158, v137 offset:1152
	ds_read_b32 v159, v137 offset:1440
	ds_read_b32 v160, v137 offset:1728
	ds_read_b32 v161, v137 offset:2016
	s_waitcnt lgkmcnt(0)
	global_atomic_add_f32 v138, v154, s[24:25] offset:512
	global_atomic_add_f32 v139, v155, s[24:25] offset:512
	global_atomic_add_f32 v140, v156, s[24:25] offset:512
	global_atomic_add_f32 v141, v157, s[24:25] offset:512
	global_atomic_add_f32 v142, v158, s[24:25] offset:512
	global_atomic_add_f32 v143, v159, s[24:25] offset:512
	global_atomic_add_f32 v144, v160, s[24:25] offset:512
	global_atomic_add_f32 v145, v161, s[24:25] offset:512
.Lg4s_q6:
	s_cmp_lg_u32 s5, 6
	s_cbranch_scc1 .Lg4s_q7
	v_add_u32_e32 v138, 0xa0000, v134
	v_add_u32_e32 v139, 0xa2000, v134
	v_add_u32_e32 v140, 0xa4000, v134
	v_add_u32_e32 v141, 0xa6000, v134
	v_add_u32_e32 v142, 0xa8000, v134
	v_add_u32_e32 v143, 0xaa000, v134
	v_add_u32_e32 v144, 0xac000, v134
	v_add_u32_e32 v145, 0xae000, v134
	ds_write_b128 v136, v[38:41]
	ds_write_b128 v136, v[34:37] offset:64
	ds_read_b32 v146, v137
	ds_read_b32 v147, v137 offset:288
	ds_read_b32 v148, v137 offset:576
	ds_read_b32 v149, v137 offset:864
	ds_read_b32 v150, v137 offset:1152
	ds_read_b32 v151, v137 offset:1440
	ds_read_b32 v152, v137 offset:1728
	ds_read_b32 v153, v137 offset:2016
	s_waitcnt lgkmcnt(0)
	global_atomic_add_f32 v138, v146, s[24:25]
	global_atomic_add_f32 v139, v147, s[24:25]
	global_atomic_add_f32 v140, v148, s[24:25]
	global_atomic_add_f32 v141, v149, s[24:25]
	global_atomic_add_f32 v142, v150, s[24:25]
	global_atomic_add_f32 v143, v151, s[24:25]
	global_atomic_add_f32 v144, v152, s[24:25]
	global_atomic_add_f32 v145, v153, s[24:25]
	ds_write_b128 v136, v[14:17]
	ds_write_b128 v136, v[10:13] offset:64
	ds_read_b32 v154, v137
	ds_read_b32 v155, v137 offset:288
	ds_read_b32 v156, v137 offset:576
	ds_read_b32 v157, v137 offset:864
	ds_read_b32 v158, v137 offset:1152
	ds_read_b32 v159, v137 offset:1440
	ds_read_b32 v160, v137 offset:1728
	ds_read_b32 v161, v137 offset:2016
	s_waitcnt lgkmcnt(0)
	global_atomic_add_f32 v138, v154, s[24:25] offset:512
	global_atomic_add_f32 v139, v155, s[24:25] offset:512
	global_atomic_add_f32 v140, v156, s[24:25] offset:512
	global_atomic_add_f32 v141, v157, s[24:25] offset:512
	global_atomic_add_f32 v142, v158, s[24:25] offset:512
	global_atomic_add_f32 v143, v159, s[24:25] offset:512
	global_atomic_add_f32 v144, v160, s[24:25] offset:512
	global_atomic_add_f32 v145, v161, s[24:25] offset:512
.Lg4s_q7:
	s_cmp_lg_u32 s5, 7
	s_cbranch_scc1 .Lg4s_q8
	v_add_u32_e32 v138, 0xb0000, v134
	v_add_u32_e32 v139, 0xb2000, v134
	v_add_u32_e32 v140, 0xb4000, v134
	v_add_u32_e32 v141, 0xb6000, v134
	v_add_u32_e32 v142, 0xb8000, v134
	v_add_u32_e32 v143, 0xba000, v134
	v_add_u32_e32 v144, 0xbc000, v134
	v_add_u32_e32 v145, 0xbe000, v134
	ds_write_b128 v136, v[22:25]
	ds_write_b128 v136, v[18:21] offset:64
	ds_read_b32 v146, v137
	ds_read_b32 v147, v137 offset:288
	ds_read_b32 v148, v137 offset:576
	ds_read_b32 v149, v137 offset:864
	ds_read_b32 v150, v137 offset:1152
	ds_read_b32 v151, v137 offset:1440
	ds_read_b32 v152, v137 offset:1728
	ds_read_b32 v153, v137 offset:2016
	s_waitcnt lgkmcnt(0)
	global_atomic_add_f32 v138, v146, s[24:25]
	global_atomic_add_f32 v139, v147, s[24:25]
	global_atomic_add_f32 v140, v148, s[24:25]
	global_atomic_add_f32 v141, v149, s[24:25]
	global_atomic_add_f32 v142, v150, s[24:25]
	global_atomic_add_f32 v143, v151, s[24:25]
	global_atomic_add_f32 v144, v152, s[24:25]
	global_atomic_add_f32 v145, v153, s[24:25]
	ds_write_b128 v136, v[6:9]
	ds_write_b128 v136, v[2:5] offset:64
	ds_read_b32 v154, v137
	ds_read_b32 v155, v137 offset:288
	ds_read_b32 v156, v137 offset:576
	ds_read_b32 v157, v137 offset:864
	ds_read_b32 v158, v137 offset:1152
	ds_read_b32 v159, v137 offset:1440
	ds_read_b32 v160, v137 offset:1728
	ds_read_b32 v161, v137 offset:2016
	s_waitcnt lgkmcnt(0)
	global_atomic_add_f32 v138, v154, s[24:25] offset:512
	global_atomic_add_f32 v139, v155, s[24:25] offset:512
	global_atomic_add_f32 v140, v156, s[24:25] offset:512
	global_atomic_add_f32 v141, v157, s[24:25] offset:512
	global_atomic_add_f32 v142, v158, s[24:25] offset:512
	global_atomic_add_f32 v143, v159, s[24:25] offset:512
	global_atomic_add_f32 v144, v160, s[24:25] offset:512
	global_atomic_add_f32 v145, v161, s[24:25] offset:512

	.amdhsa_kernel _Z6mk_fwd4Args
		.amdhsa_group_segment_fixed_size 4096
		.amdhsa_private_segment_fixed_size 0
		.amdhsa_kernarg_size 480
		.amdhsa_user_sgpr_count 2
		.amdhsa_user_sgpr_dispatch_ptr 0
		.amdhsa_user_sgpr_queue_ptr 0
		.amdhsa_user_sgpr_kernarg_segment_ptr 1
		.amdhsa_user_sgpr_dispatch_id 0
		.amdhsa_user_sgpr_kernarg_preload_length 0
		.amdhsa_user_sgpr_kernarg_preload_offset 0
		.amdhsa_user_sgpr_private_segment_size 0
		.amdhsa_uses_dynamic_stack 0
		.amdhsa_enable_private_segment 0
		.amdhsa_system_sgpr_workgroup_id_x 1
		.amdhsa_system_sgpr_workgroup_id_y 0
		.amdhsa_system_sgpr_workgroup_id_z 0
		.amdhsa_system_sgpr_workgroup_info 0
		.amdhsa_system_vgpr_workitem_id 2
		.amdhsa_next_free_vgpr 256
		.amdhsa_next_free_sgpr 100
		.amdhsa_accum_offset 256
		.amdhsa_reserve_vcc 1
		.amdhsa_float_round_mode_32 0
		.amdhsa_float_round_mode_16_64 0
		.amdhsa_float_denorm_mode_32 3
		.amdhsa_float_denorm_mode_16_64 3
		.amdhsa_dx10_clamp 1
		.amdhsa_ieee_mode 1
		.amdhsa_fp16_overflow 0
		.amdhsa_tg_split 0
		.amdhsa_exception_fp_ieee_invalid_op 0
		.amdhsa_exception_fp_denorm_src 0
		.amdhsa_exception_fp_ieee_div_zero 0
		.amdhsa_exception_fp_ieee_overflow 0
		.amdhsa_exception_fp_ieee_underflow 0
		.amdhsa_exception_fp_ieee_inexact 0
		.amdhsa_exception_int_div_zero 0
	.end_amdhsa_kernel

amdhsa.kernels:
  - .agpr_count:     0
    .args:
      - .offset:         0
        .size:           224
        .value_kind:     by_value
      - .offset:         224
        .size:           4
        .value_kind:     hidden_block_count_x
      - .offset:         228
        .size:           4
        .value_kind:     hidden_block_count_y
      - .offset:         232
        .size:           4
        .value_kind:     hidden_block_count_z
      - .offset:         236
        .size:           2
        .value_kind:     hidden_group_size_x
      - .offset:         238
        .size:           2
        .value_kind:     hidden_group_size_y
      - .offset:         240
        .size:           2
        .value_kind:     hidden_group_size_z
      - .offset:         242
        .size:           2
        .value_kind:     hidden_remainder_x
      - .offset:         244
        .size:           2
        .value_kind:     hidden_remainder_y
      - .offset:         246
        .size:           2
        .value_kind:     hidden_remainder_z
      - .offset:         264
        .size:           8
        .value_kind:     hidden_global_offset_x
      - .offset:         272
        .size:           8
        .value_kind:     hidden_global_offset_y
      - .offset:         280
        .size:           8
        .value_kind:     hidden_global_offset_z
      - .offset:         288
        .size:           2
        .value_kind:     hidden_grid_dims
      - .offset:         312
        .size:           8
        .value_kind:     hidden_multigrid_sync_arg
      - .offset:         344
        .size:           4
        .value_kind:     hidden_dynamic_lds_size
    .group_segment_fixed_size: 4096
    .kernarg_segment_align: 8
    .kernarg_segment_size: 480
    .language:       OpenCL C
    .language_version:
      - 2
      - 0
    .max_flat_workgroup_size: 512
    .name:           _Z6mk_fwd4Args
    .private_segment_fixed_size: 0
    .sgpr_count:     106
    .sgpr_spill_count: 191
    .symbol:         _Z6mk_fwd4Args.kd
    .uniform_work_group_size: 1
    .uses_dynamic_stack: false
    .vgpr_count:     256
    .vgpr_spill_count: 0
    .wavefront_size: 64
